# grid barrier: first workgroup of an XCD to arrive starts an L2 write-back (no wait) so the leader's release write-back has less to flush
# baseline (speedup 1.0000x reference)
.LBB0_692:
	s_or_b64 exec, exec, s[12:13]
	v_cvt_f32_u32_e32 v5, v3
	s_waitcnt vmcnt(0)
	v_readfirstlane_b32 s2, v4
	v_sub_u32_e32 v4, 0, v3
	v_rcp_iflag_f32_e32 v5, v5
	v_add_u32_e32 v6, s2, v2
	v_mul_f32_e32 v5, 0x4f7ffffe, v5
	v_cvt_u32_f32_e32 v5, v5
	v_mul_lo_u32 v2, v4, v5
	v_mul_hi_u32 v2, v5, v2
	v_add_u32_e32 v2, v5, v2
	v_mul_hi_u32 v2, v6, v2
	v_mul_lo_u32 v4, v2, v3
	v_sub_u32_e32 v4, v6, v4
	v_add_u32_e32 v5, 1, v2
	v_cmp_ge_u32_e32 vcc, v4, v3
	s_nop 1
	v_cndmask_b32_e32 v2, v2, v5, vcc
	v_sub_u32_e32 v5, v4, v3
	v_cndmask_b32_e32 v4, v4, v5, vcc
	v_add_u32_e32 v5, 1, v2
	v_cmp_ge_u32_e32 vcc, v4, v3
	v_add_u32_e32 v4, 1, v6
	s_nop 0
	v_cndmask_b32_e32 v2, v2, v5, vcc
	v_mul_lo_u32 v5, v3, v2
	v_add_u32_e32 v3, v5, v3
	v_cmp_ne_u32_e32 vcc, v4, v3
	s_and_saveexec_b64 s[2:3], vcc
	s_xor_b64 s[10:11], exec, s[2:3]
	s_cbranch_execz .LBB0_706
	v_cmp_eq_u32_e32 vcc, v6, v5
	s_and_saveexec_b64 s[98:99], vcc
	s_cbranch_execz .Lmy_bar0_nf
	buffer_wbl2 sc1
.Lmy_bar0_nf:
	s_or_b64 exec, exec, s[98:99]
	s_waitcnt lgkmcnt(0)
	v_mov_b32_e32 v1, 0x2000
	buffer_inv sc1
	global_load_dword v1, v1, s[8:9] offset:1024 sc1
	s_add_u32 s16, s8, 0x2400
	s_addc_u32 s17, s9, 0
	s_waitcnt vmcnt(0)
	v_cmp_eq_u32_e32 vcc, v1, v2
	s_and_saveexec_b64 s[12:13], vcc
	s_cbranch_execz .LBB0_705
	s_add_u32 s14, s94, 0x4200
	s_addc_u32 s15, s95, 0
	s_mov_b32 s2, 1
	s_mov_b64 s[18:19], 0
	v_mov_b32_e32 v1, 0
	s_branch .LBB0_696

.LBB0_754:
	s_or_b64 exec, exec, s[10:11]
	v_cvt_f32_u32_e32 v5, v3
	s_waitcnt vmcnt(0)
	v_readfirstlane_b32 s5, v4
	v_sub_u32_e32 v4, 0, v3
	v_rcp_iflag_f32_e32 v5, v5
	v_add_u32_e32 v6, s5, v2
	v_mul_f32_e32 v5, 0x4f7ffffe, v5
	v_cvt_u32_f32_e32 v5, v5
	v_mul_lo_u32 v2, v4, v5
	v_mul_hi_u32 v2, v5, v2
	v_add_u32_e32 v2, v5, v2
	v_mul_hi_u32 v2, v6, v2
	v_mul_lo_u32 v4, v2, v3
	v_sub_u32_e32 v4, v6, v4
	v_add_u32_e32 v5, 1, v2
	v_cmp_ge_u32_e32 vcc, v4, v3
	s_nop 1
	v_cndmask_b32_e32 v2, v2, v5, vcc
	v_sub_u32_e32 v5, v4, v3
	v_cndmask_b32_e32 v4, v4, v5, vcc
	v_add_u32_e32 v5, 1, v2
	v_cmp_ge_u32_e32 vcc, v4, v3
	v_add_u32_e32 v4, 1, v6
	s_nop 0
	v_cndmask_b32_e32 v2, v2, v5, vcc
	v_mul_lo_u32 v5, v3, v2
	v_add_u32_e32 v3, v5, v3
	v_cmp_ne_u32_e32 vcc, v4, v3
	s_and_saveexec_b64 s[8:9], vcc
	s_xor_b64 s[8:9], exec, s[8:9]
	s_cbranch_execz .LBB0_768
	v_cmp_eq_u32_e32 vcc, v6, v5
	s_and_saveexec_b64 s[98:99], vcc
	s_cbranch_execz .Lmy_bar1_nf
	buffer_wbl2 sc1
.Lmy_bar1_nf:
	s_or_b64 exec, exec, s[98:99]
	s_add_i32 s10, s4, 0x900
	s_mov_b32 s11, 0
	s_lshl_b64 s[10:11], s[10:11], 2
	v_readlane_b32 s5, v228, 8
	s_add_u32 s16, s5, s10
	v_readlane_b32 s5, v228, 10
	s_addc_u32 s17, s5, s11
	s_waitcnt lgkmcnt(0)
	v_mov_b32_e32 v1, 0
	buffer_inv sc1
	global_load_dword v3, v1, s[16:17] sc1
	s_waitcnt vmcnt(0)
	v_cmp_eq_u32_e32 vcc, v3, v2
	s_and_saveexec_b64 s[10:11], vcc
	s_cbranch_execz .LBB0_767
	s_add_u32 s14, s38, 0x4200
	s_addc_u32 s15, s39, 0
	s_mov_b32 s5, 1
	s_mov_b64 s[18:19], 0
	s_branch .LBB0_758

.LBB0_901:
	s_or_b64 exec, exec, s[14:15]
	v_cvt_f32_u32_e32 v5, v3
	s_waitcnt vmcnt(0)
	v_readfirstlane_b32 s5, v4
	v_sub_u32_e32 v4, 0, v3
	v_rcp_iflag_f32_e32 v5, v5
	v_add_u32_e32 v6, s5, v2
	v_mul_f32_e32 v5, 0x4f7ffffe, v5
	v_cvt_u32_f32_e32 v5, v5
	v_mul_lo_u32 v2, v4, v5
	v_mul_hi_u32 v2, v5, v2
	v_add_u32_e32 v2, v5, v2
	v_mul_hi_u32 v2, v6, v2
	v_mul_lo_u32 v4, v2, v3
	v_sub_u32_e32 v4, v6, v4
	v_add_u32_e32 v5, 1, v2
	v_cmp_ge_u32_e32 vcc, v4, v3
	s_nop 1
	v_cndmask_b32_e32 v2, v2, v5, vcc
	v_sub_u32_e32 v5, v4, v3
	v_cndmask_b32_e32 v4, v4, v5, vcc
	v_add_u32_e32 v5, 1, v2
	v_cmp_ge_u32_e32 vcc, v4, v3
	v_add_u32_e32 v4, 1, v6
	s_nop 0
	v_cndmask_b32_e32 v2, v2, v5, vcc
	v_mul_lo_u32 v5, v3, v2
	v_add_u32_e32 v3, v5, v3
	v_cmp_ne_u32_e32 vcc, v4, v3
	s_and_saveexec_b64 s[10:11], vcc
	s_xor_b64 s[10:11], exec, s[10:11]
	s_cbranch_execz .LBB0_915
	v_cmp_eq_u32_e32 vcc, v6, v5
	s_and_saveexec_b64 s[98:99], vcc
	s_cbranch_execz .Lmy_bar2_nf
	buffer_wbl2 sc1
.Lmy_bar2_nf:
	s_or_b64 exec, exec, s[98:99]
	s_add_i32 s14, s4, 0x900
	s_mov_b32 s15, 0
	s_lshl_b64 s[14:15], s[14:15], 2
	v_readlane_b32 s5, v228, 8
	s_add_u32 s18, s5, s14
	v_readlane_b32 s5, v228, 10
	s_addc_u32 s19, s5, s15
	s_waitcnt lgkmcnt(0)
	v_mov_b32_e32 v1, 0
	buffer_inv sc1
	global_load_dword v3, v1, s[18:19] sc1
	s_waitcnt vmcnt(0)
	v_cmp_eq_u32_e32 vcc, v3, v2
	s_and_saveexec_b64 s[14:15], vcc
	s_cbranch_execz .LBB0_914
	s_add_u32 s16, s38, 0x4200
	s_addc_u32 s17, s39, 0
	s_mov_b32 s5, 1
	s_mov_b64 s[20:21], 0
	s_branch .LBB0_905

.LBB0_1024:
	s_or_b64 exec, exec, s[10:11]
	v_cvt_f32_u32_e32 v5, v3
	s_waitcnt vmcnt(0)
	v_readfirstlane_b32 s4, v4
	v_sub_u32_e32 v4, 0, v3
	v_rcp_iflag_f32_e32 v5, v5
	v_add_u32_e32 v6, s4, v2
	v_mul_f32_e32 v5, 0x4f7ffffe, v5
	v_cvt_u32_f32_e32 v5, v5
	v_mul_lo_u32 v2, v4, v5
	v_mul_hi_u32 v2, v5, v2
	v_add_u32_e32 v2, v5, v2
	v_mul_hi_u32 v2, v6, v2
	v_mul_lo_u32 v4, v2, v3
	v_sub_u32_e32 v4, v6, v4
	v_add_u32_e32 v5, 1, v2
	v_cmp_ge_u32_e32 vcc, v4, v3
	s_nop 1
	v_cndmask_b32_e32 v2, v2, v5, vcc
	v_sub_u32_e32 v5, v4, v3
	v_cndmask_b32_e32 v4, v4, v5, vcc
	v_add_u32_e32 v5, 1, v2
	v_cmp_ge_u32_e32 vcc, v4, v3
	v_add_u32_e32 v4, 1, v6
	s_nop 0
	v_cndmask_b32_e32 v2, v2, v5, vcc
	v_mul_lo_u32 v5, v3, v2
	v_add_u32_e32 v3, v5, v3
	v_cmp_ne_u32_e32 vcc, v4, v3
	s_and_saveexec_b64 s[4:5], vcc
	s_xor_b64 s[8:9], exec, s[4:5]
	s_cbranch_execz .LBB0_1038
	v_cmp_eq_u32_e32 vcc, v6, v5
	s_and_saveexec_b64 s[98:99], vcc
	s_cbranch_execz .Lmy_bar3_nf
	buffer_wbl2 sc1
.Lmy_bar3_nf:
	s_or_b64 exec, exec, s[98:99]
	s_add_i32 s4, s2, 0x900
	s_mov_b32 s5, 0
	s_lshl_b64 s[4:5], s[4:5], 2
	v_readlane_b32 s10, v228, 8
	s_add_u32 s16, s10, s4
	v_readlane_b32 s4, v228, 10
	s_addc_u32 s17, s4, s5
	s_waitcnt lgkmcnt(0)
	v_mov_b32_e32 v1, 0
	buffer_inv sc1
	global_load_dword v3, v1, s[16:17] sc1
	s_waitcnt vmcnt(0)
	v_cmp_eq_u32_e32 vcc, v3, v2
	s_and_saveexec_b64 s[10:11], vcc
	s_cbranch_execz .LBB0_1037
	s_add_u32 s14, s38, 0x4200
	s_addc_u32 s15, s39, 0
	s_mov_b32 s4, 1
	s_mov_b64 s[18:19], 0
	s_branch .LBB0_1028

.Lmy_bar5_nf:
	s_or_b64 exec, exec, s[98:99]
	s_add_i32 s4, s2, 0x900
	s_mov_b32 s5, 0
	s_lshl_b64 s[4:5], s[4:5], 2
	v_readlane_b32 s10, v228, 8
	s_add_u32 s14, s10, s4
	v_readlane_b32 s4, v228, 10
	s_addc_u32 s15, s4, s5
	s_waitcnt lgkmcnt(0)
	v_mov_b32_e32 v1, 0
	buffer_inv sc1
	global_load_dword v3, v1, s[14:15] sc1
	s_waitcnt vmcnt(0)
	v_cmp_eq_u32_e32 vcc, v3, v2
	s_and_saveexec_b64 s[10:11], vcc
	s_cbranch_execz .LBB0_1689
	s_add_u32 s12, s38, 0x4200
	s_addc_u32 s13, s39, 0
	s_mov_b32 s4, 1
	s_mov_b64 s[16:17], 0
	s_branch .LBB0_1680

.LBB0_2223:
	s_or_b64 exec, exec, s[10:11]
	v_cvt_f32_u32_e32 v5, v3
	s_waitcnt vmcnt(0)
	v_readfirstlane_b32 s3, v4
	v_sub_u32_e32 v4, 0, v3
	v_rcp_iflag_f32_e32 v5, v5
	v_add_u32_e32 v6, s3, v2
	v_mul_f32_e32 v5, 0x4f7ffffe, v5
	v_cvt_u32_f32_e32 v5, v5
	v_mul_lo_u32 v2, v4, v5
	v_mul_hi_u32 v2, v5, v2
	v_add_u32_e32 v2, v5, v2
	v_mul_hi_u32 v2, v6, v2
	v_mul_lo_u32 v4, v2, v3
	v_sub_u32_e32 v4, v6, v4
	v_add_u32_e32 v5, 1, v2
	v_cmp_ge_u32_e32 vcc, v4, v3
	s_nop 1
	v_cndmask_b32_e32 v2, v2, v5, vcc
	v_sub_u32_e32 v5, v4, v3
	v_cndmask_b32_e32 v4, v4, v5, vcc
	v_add_u32_e32 v5, 1, v2
	v_cmp_ge_u32_e32 vcc, v4, v3
	v_add_u32_e32 v4, 1, v6
	s_nop 0
	v_cndmask_b32_e32 v2, v2, v5, vcc
	v_mul_lo_u32 v5, v3, v2
	v_add_u32_e32 v3, v5, v3
	v_cmp_ne_u32_e32 vcc, v4, v3
	s_and_saveexec_b64 s[4:5], vcc
	s_xor_b64 s[8:9], exec, s[4:5]
	s_cbranch_execz .LBB0_2237
	v_cmp_eq_u32_e32 vcc, v6, v5
	s_and_saveexec_b64 s[98:99], vcc
	s_cbranch_execz .Lmy_bar6_nf
	buffer_wbl2 sc1
.Lmy_bar6_nf:
	s_or_b64 exec, exec, s[98:99]
	s_add_i32 s4, s2, 0x900
	s_mov_b32 s5, 0
	s_lshl_b64 s[4:5], s[4:5], 2
	v_readlane_b32 s3, v228, 8
	s_add_u32 s14, s3, s4
	v_readlane_b32 s3, v228, 10
	s_addc_u32 s15, s3, s5
	s_waitcnt lgkmcnt(0)
	v_mov_b32_e32 v1, 0
	buffer_inv sc1
	global_load_dword v3, v1, s[14:15] sc1
	s_waitcnt vmcnt(0)
	v_cmp_eq_u32_e32 vcc, v3, v2
	s_and_saveexec_b64 s[10:11], vcc
	s_cbranch_execz .LBB0_2236
	s_add_u32 s12, s38, 0x4200
	s_addc_u32 s13, s39, 0
	s_mov_b32 s3, 1
	s_mov_b64 s[16:17], 0
	s_branch .LBB0_2227

.LBB0_2987:
	s_or_b64 exec, exec, s[12:13]
	v_cvt_f32_u32_e32 v5, v3
	s_waitcnt vmcnt(0)
	v_readfirstlane_b32 s3, v4
	v_sub_u32_e32 v4, 0, v3
	v_rcp_iflag_f32_e32 v5, v5
	v_add_u32_e32 v6, s3, v2
	v_mul_f32_e32 v5, 0x4f7ffffe, v5
	v_cvt_u32_f32_e32 v5, v5
	v_mul_lo_u32 v2, v4, v5
	v_mul_hi_u32 v2, v5, v2
	v_add_u32_e32 v2, v5, v2
	v_mul_hi_u32 v2, v6, v2
	v_mul_lo_u32 v4, v2, v3
	v_sub_u32_e32 v4, v6, v4
	v_add_u32_e32 v5, 1, v2
	v_cmp_ge_u32_e32 vcc, v4, v3
	s_nop 1
	v_cndmask_b32_e32 v2, v2, v5, vcc
	v_sub_u32_e32 v5, v4, v3
	v_cndmask_b32_e32 v4, v4, v5, vcc
	v_add_u32_e32 v5, 1, v2
	v_cmp_ge_u32_e32 vcc, v4, v3
	v_add_u32_e32 v4, 1, v6
	s_nop 0
	v_cndmask_b32_e32 v2, v2, v5, vcc
	v_mul_lo_u32 v5, v3, v2
	v_add_u32_e32 v3, v5, v3
	v_cmp_ne_u32_e32 vcc, v4, v3
	s_and_saveexec_b64 s[10:11], vcc
	s_xor_b64 s[10:11], exec, s[10:11]
	s_cbranch_execz .LBB0_3001
	v_cmp_eq_u32_e32 vcc, v6, v5
	s_and_saveexec_b64 s[98:99], vcc
	s_cbranch_execz .Lmy_bar7_nf
	buffer_wbl2 sc1
.Lmy_bar7_nf:
	s_or_b64 exec, exec, s[98:99]
	s_add_i32 s12, s2, 0x900
	s_mov_b32 s13, 0
	s_lshl_b64 s[12:13], s[12:13], 2
	v_readlane_b32 s3, v228, 8
	s_add_u32 s16, s3, s12
	v_readlane_b32 s3, v228, 10
	s_addc_u32 s17, s3, s13
	s_waitcnt lgkmcnt(0)
	v_mov_b32_e32 v1, 0
	buffer_inv sc1
	global_load_dword v3, v1, s[16:17] sc1
	s_waitcnt vmcnt(0)
	v_cmp_eq_u32_e32 vcc, v3, v2
	s_and_saveexec_b64 s[12:13], vcc
	s_cbranch_execz .LBB0_3000
	s_add_u32 s14, s38, 0x4200
	s_addc_u32 s15, s39, 0
	s_mov_b32 s3, 1
	s_mov_b64 s[18:19], 0
	s_branch .LBB0_2991

.LBB0_3238:
	s_or_b64 exec, exec, s[20:21]
	v_cvt_f32_u32_e32 v5, v3
	s_waitcnt vmcnt(0)
	v_readfirstlane_b32 s10, v4
	v_sub_u32_e32 v4, 0, v3
	v_rcp_iflag_f32_e32 v5, v5
	v_add_u32_e32 v6, s10, v2
	v_mul_f32_e32 v5, 0x4f7ffffe, v5
	v_cvt_u32_f32_e32 v5, v5
	v_mul_lo_u32 v2, v4, v5
	v_mul_hi_u32 v2, v5, v2
	v_add_u32_e32 v2, v5, v2
	v_mul_hi_u32 v2, v6, v2
	v_mul_lo_u32 v4, v2, v3
	v_sub_u32_e32 v4, v6, v4
	v_add_u32_e32 v5, 1, v2
	v_cmp_ge_u32_e32 vcc, v4, v3
	s_nop 1
	v_cndmask_b32_e32 v2, v2, v5, vcc
	v_sub_u32_e32 v5, v4, v3
	v_cndmask_b32_e32 v4, v4, v5, vcc
	v_add_u32_e32 v5, 1, v2
	v_cmp_ge_u32_e32 vcc, v4, v3
	v_add_u32_e32 v4, 1, v6
	s_nop 0
	v_cndmask_b32_e32 v2, v2, v5, vcc
	v_mul_lo_u32 v5, v3, v2
	v_add_u32_e32 v3, v5, v3
	v_cmp_ne_u32_e32 vcc, v4, v3
	s_and_saveexec_b64 s[10:11], vcc
	s_xor_b64 s[10:11], exec, s[10:11]
	s_cbranch_execz .LBB0_3252
	v_cmp_eq_u32_e32 vcc, v6, v5
	s_and_saveexec_b64 s[98:99], vcc
	s_cbranch_execz .Lmy_bar9_nf
	buffer_wbl2 sc1
.Lmy_bar9_nf:
	s_or_b64 exec, exec, s[98:99]
	s_add_i32 s20, s17, 0x900
	s_mov_b32 s21, 0
	s_lshl_b64 s[20:21], s[20:21], 2
	s_add_u32 s24, s3, s20
	s_addc_u32 s25, s4, s21
	s_waitcnt lgkmcnt(0)
	v_mov_b32_e32 v1, 0
	buffer_inv sc1
	global_load_dword v3, v1, s[24:25] sc1
	s_waitcnt vmcnt(0)
	v_cmp_eq_u32_e32 vcc, v3, v2
	s_and_saveexec_b64 s[20:21], vcc
	s_cbranch_execz .LBB0_3251
	s_add_u32 s22, s12, 0x4200
	s_addc_u32 s23, s13, 0
	s_mov_b32 s28, 1
	s_mov_b64 s[26:27], 0
	s_branch .LBB0_3242

.Lmy_bar10_nf:
	s_or_b64 exec, exec, s[98:99]
	s_add_i32 s10, s2, 0x900
	s_mov_b32 s11, 0
	s_lshl_b64 s[10:11], s[10:11], 2
	s_add_u32 s16, s3, s10
	s_addc_u32 s17, s4, s11
	s_waitcnt lgkmcnt(0)
	v_mov_b32_e32 v1, 0
	buffer_inv sc1
	global_load_dword v3, v1, s[16:17] sc1
	s_waitcnt vmcnt(0)
	v_cmp_eq_u32_e32 vcc, v3, v2
	s_and_saveexec_b64 s[10:11], vcc
	s_cbranch_execz .LBB0_3374
	s_add_u32 s14, s12, 0x4200
	s_addc_u32 s15, s13, 0
	s_mov_b32 s5, 1
	s_mov_b64 s[18:19], 0
	s_branch .LBB0_3365

.LBB0_3508:
	s_or_b64 exec, exec, s[16:17]
	v_cvt_f32_u32_e32 v5, v3
	s_waitcnt vmcnt(0)
	v_readfirstlane_b32 s4, v4
	v_sub_u32_e32 v4, 0, v3
	v_rcp_iflag_f32_e32 v5, v5
	v_add_u32_e32 v6, s4, v2
	v_mul_f32_e32 v5, 0x4f7ffffe, v5
	v_cvt_u32_f32_e32 v5, v5
	v_mul_lo_u32 v2, v4, v5
	v_mul_hi_u32 v2, v5, v2
	v_add_u32_e32 v2, v5, v2
	v_mul_hi_u32 v2, v6, v2
	v_mul_lo_u32 v4, v2, v3
	v_sub_u32_e32 v4, v6, v4
	v_add_u32_e32 v5, 1, v2
	v_cmp_ge_u32_e32 vcc, v4, v3
	s_nop 1
	v_cndmask_b32_e32 v2, v2, v5, vcc
	v_sub_u32_e32 v5, v4, v3
	v_cndmask_b32_e32 v4, v4, v5, vcc
	v_add_u32_e32 v5, 1, v2
	v_cmp_ge_u32_e32 vcc, v4, v3
	v_add_u32_e32 v4, 1, v6
	s_nop 0
	v_cndmask_b32_e32 v2, v2, v5, vcc
	v_mul_lo_u32 v5, v3, v2
	v_add_u32_e32 v3, v5, v3
	v_cmp_ne_u32_e32 vcc, v4, v3
	s_and_saveexec_b64 s[4:5], vcc
	s_xor_b64 s[10:11], exec, s[4:5]
	s_cbranch_execz .LBB0_3522
	v_cmp_eq_u32_e32 vcc, v6, v5
	s_and_saveexec_b64 s[98:99], vcc
	s_cbranch_execz .Lmy_bar11_nf
	buffer_wbl2 sc1
.Lmy_bar11_nf:
	s_or_b64 exec, exec, s[98:99]
	s_add_i32 s4, s3, 0x900
	s_mov_b32 s5, 0
	s_lshl_b64 s[4:5], s[4:5], 2
	v_readlane_b32 s13, v228, 19
	s_add_u32 s20, s13, s4
	v_readlane_b32 s4, v228, 23
	s_addc_u32 s21, s4, s5
	s_waitcnt lgkmcnt(0)
	v_mov_b32_e32 v1, 0
	buffer_inv sc1
	global_load_dword v3, v1, s[20:21] sc1
	s_waitcnt vmcnt(0)
	v_cmp_eq_u32_e32 vcc, v3, v2
	s_and_saveexec_b64 s[16:17], vcc
	s_cbranch_execz .LBB0_3521
	s_add_u32 s18, s38, 0x4200
	s_addc_u32 s19, s39, 0
	s_mov_b32 s4, 1
	s_mov_b64 s[22:23], 0
	s_branch .LBB0_3512

.Lmy_bar12_nf:
	s_or_b64 exec, exec, s[98:99]
	s_add_i32 s4, s2, 0x900
	s_mov_b32 s5, 0
	s_lshl_b64 s[4:5], s[4:5], 2
	v_readlane_b32 s3, v228, 19
	s_add_u32 s16, s3, s4
	v_readlane_b32 s3, v228, 23
	s_addc_u32 s17, s3, s5
	s_waitcnt lgkmcnt(0)
	v_mov_b32_e32 v1, 0
	buffer_inv sc1
	global_load_dword v3, v1, s[16:17] sc1
	s_waitcnt vmcnt(0)
	v_cmp_eq_u32_e32 vcc, v3, v2
	s_and_saveexec_b64 s[10:11], vcc
	s_cbranch_execz .LBB0_3644
	s_add_u32 s14, s38, 0x4200
	s_addc_u32 s15, s39, 0
	s_mov_b32 s3, 1
	s_mov_b64 s[18:19], 0
	s_branch .LBB0_3635

.Lmy_bar14_nf:
	s_or_b64 exec, exec, s[98:99]
	s_add_i32 s4, s2, 0x900
	s_mov_b32 s5, 0
	s_lshl_b64 s[4:5], s[4:5], 2
	v_readlane_b32 s3, v228, 19
	s_add_u32 s14, s3, s4
	v_readlane_b32 s3, v228, 23
	s_addc_u32 s15, s3, s5
	s_waitcnt lgkmcnt(0)
	v_mov_b32_e32 v1, 0
	buffer_inv sc1
	global_load_dword v3, v1, s[14:15] sc1
	s_waitcnt vmcnt(0)
	v_cmp_eq_u32_e32 vcc, v3, v2
	s_and_saveexec_b64 s[10:11], vcc
	s_cbranch_execz .LBB0_4296
	s_add_u32 s12, s38, 0x4200
	s_addc_u32 s13, s39, 0
	s_mov_b32 s3, 1
	s_mov_b64 s[16:17], 0
	s_branch .LBB0_4287

.Lmy_bar16_nf:
	s_or_b64 exec, exec, s[98:99]
	s_add_i32 s12, s2, 0x900
	s_mov_b32 s13, 0
	s_lshl_b64 s[12:13], s[12:13], 2
	v_readlane_b32 s3, v228, 19
	s_add_u32 s16, s3, s12
	v_readlane_b32 s3, v228, 23
	s_addc_u32 s17, s3, s13
	s_waitcnt lgkmcnt(0)
	v_mov_b32_e32 v1, 0
	buffer_inv sc1
	global_load_dword v3, v1, s[16:17] sc1
	s_waitcnt vmcnt(0)
	v_cmp_eq_u32_e32 vcc, v3, v2
	s_and_saveexec_b64 s[12:13], vcc
	s_cbranch_execz .LBB0_5607
	s_add_u32 s14, s38, 0x4200
	s_addc_u32 s15, s39, 0
	s_mov_b32 s3, 1
	s_mov_b64 s[18:19], 0
	s_branch .LBB0_5598

.LBB0_5845:
	s_or_b64 exec, exec, s[12:13]
	v_cvt_f32_u32_e32 v5, v3
	s_waitcnt vmcnt(0)
	v_readfirstlane_b32 s10, v4
	v_sub_u32_e32 v4, 0, v3
	v_rcp_iflag_f32_e32 v5, v5
	v_add_u32_e32 v6, s10, v2
	v_mul_f32_e32 v5, 0x4f7ffffe, v5
	v_cvt_u32_f32_e32 v5, v5
	v_mul_lo_u32 v2, v4, v5
	v_mul_hi_u32 v2, v5, v2
	v_add_u32_e32 v2, v5, v2
	v_mul_hi_u32 v2, v6, v2
	v_mul_lo_u32 v4, v2, v3
	v_sub_u32_e32 v4, v6, v4
	v_add_u32_e32 v5, 1, v2
	v_cmp_ge_u32_e32 vcc, v4, v3
	s_nop 1
	v_cndmask_b32_e32 v2, v2, v5, vcc
	v_sub_u32_e32 v5, v4, v3
	v_cndmask_b32_e32 v4, v4, v5, vcc
	v_add_u32_e32 v5, 1, v2
	v_cmp_ge_u32_e32 vcc, v4, v3
	v_add_u32_e32 v4, 1, v6
	s_nop 0
	v_cndmask_b32_e32 v2, v2, v5, vcc
	v_mul_lo_u32 v5, v3, v2
	v_add_u32_e32 v3, v5, v3
	v_cmp_ne_u32_e32 vcc, v4, v3
	s_and_saveexec_b64 s[10:11], vcc
	s_xor_b64 s[10:11], exec, s[10:11]
	s_cbranch_execz .LBB0_5859
	v_cmp_eq_u32_e32 vcc, v6, v5
	s_and_saveexec_b64 s[98:99], vcc
	s_cbranch_execz .Lmy_bar18_nf
	buffer_wbl2 sc1
.Lmy_bar18_nf:
	s_or_b64 exec, exec, s[98:99]
	s_add_i32 s12, s5, 0x900
	s_mov_b32 s13, 0
	s_lshl_b64 s[12:13], s[12:13], 2
	s_add_u32 s18, s3, s12
	s_addc_u32 s19, s4, s13
	s_waitcnt lgkmcnt(0)
	v_mov_b32_e32 v1, 0
	buffer_inv sc1
	global_load_dword v3, v1, s[18:19] sc1
	s_waitcnt vmcnt(0)
	v_cmp_eq_u32_e32 vcc, v3, v2
	s_and_saveexec_b64 s[12:13], vcc
	s_cbranch_execz .LBB0_5858
	s_add_u32 s16, s70, 0x4200
	s_addc_u32 s17, s71, 0
	s_mov_b32 s28, 1
	s_mov_b64 s[20:21], 0
	s_branch .LBB0_5849
